# v17
# speedup vs baseline: 1.0249x; 1.0159x over previous
; __device__ __forceinline__ unsigned xb_ld(unsigned* p)              { return __hip_atomic_load(p, __ATOMIC_RELAXED, __HIP_MEMORY_SCOPE_AGENT); }
; __device__ __forceinline__ unsigned xb_add(unsigned* p, unsigned v) { return __hip_atomic_fetch_add(p, v, __ATOMIC_RELAXED, __HIP_MEMORY_SCOPE_AGENT); }
; #define XB_SPIN(cond, bar) do { unsigned _sp = 0; while (cond) { __builtin_amdgcn_s_sleep(1); \
;     if ((++_sp & 255u) == 0u) { if (xb_ld(&(bar)[XB_TMO])) break; if (_sp > XB_SPIN_CAP) { atomicAdd(&(bar)[XB_TMO], 1u); break; } } } } while (0)
; __device__ __forceinline__ void xcd_barrier(const XcdBarrier& b) {
;     asm volatile("s_waitcnt vmcnt(0)" ::: "memory");
;     __syncthreads();
;     if (threadIdx.x == 0) {
;         unsigned* bar = b.bar;
;         __builtin_amdgcn_s_waitcnt(0);
;         unsigned nloc = b.st[0], nx = b.st[1];
;         if (nloc == 0u) { xcd_barrier_complete(bar, b.x, nloc, nx); b.st[0] = nloc; b.st[1] = nx; }
;         const unsigned old = xb_add(&bar[XB_XSUB(b.x)], 1u);
;         const unsigned gen = old / nloc;
;         if (old + 1u == (gen + 1u) * nloc) {
;             __builtin_amdgcn_fence(__ATOMIC_RELEASE, "agent");
;             asm volatile("s_waitcnt vmcnt(0)" ::: "memory");
;             const unsigned og = xb_add(&bar[XB_TOP], 1u);
;             const unsigned tg = og / nx;
;             if (og + 1u == (tg + 1u) * nx) xb_add(&bar[XB_TOPGEN], 1u);
;             else XB_SPIN(xb_ld(&bar[XB_TOPGEN]) == tg, bar);
;             __builtin_amdgcn_fence(__ATOMIC_ACQUIRE, "agent");
;             xb_add(&bar[XB_XGEN(b.x)], 1u);
;             asm volatile("s_waitcnt vmcnt(0)" ::: "memory");
;         } else {
;             XB_SPIN(xb_ld(&bar[XB_XGEN(b.x)]) == gen, bar);
;             __builtin_amdgcn_fence(__ATOMIC_ACQUIRE, "agent");
;             asm volatile("s_waitcnt vmcnt(0)" ::: "memory");
;         }
;     }
;     __syncthreads();
; }
.LBB0_907:
	s_mov_b32 s14, 0
	s_getreg_b32 s16, hwreg(HW_REG_XCC_ID, 0, 4)
	s_waitcnt vmcnt(0)
	s_waitcnt lgkmcnt(0)
	s_barrier
	s_and_saveexec_b64 s[10:11], s[4:5]
	s_cbranch_execz .LBB0_959
	v_writelane_b32 v16, s14, 0
	v_writelane_b32 v16, s15, 1
	v_writelane_b32 v16, s16, 2
	v_writelane_b32 v16, s17, 3
	v_writelane_b32 v16, s18, 4
	v_writelane_b32 v16, s19, 5
	v_writelane_b32 v16, s20, 6
	v_writelane_b32 v16, s21, 7
	v_writelane_b32 v16, s22, 8
	v_writelane_b32 v16, s23, 9
	v_writelane_b32 v16, s24, 10
	v_writelane_b32 v16, s25, 11
	v_mov_b32_e32 v10, 0x23f08
	ds_read_b32 v11, v10
	s_load_dwordx2 s[14:15], s[0:1], 0xc0
	s_waitcnt lgkmcnt(0)
	v_readfirstlane_b32 s16, v11
	s_cmp_eq_u32 s16, 1
	s_cbranch_scc1 .Llb_go_6
	s_cmp_eq_u32 s16, 2
	s_cbranch_scc1 .Llb_full_6
	s_mov_b64 s[18:19], exec
	s_mov_b64 exec, -1
	s_add_u32 s20, s14, 0x25d04000
	s_addc_u32 s21, s15, 0
	v_and_b32_e32 v2, 63, v234
	v_lshlrev_b32_e32 v3, 2, v2
	v_and_b32_e32 v9, 7, v2
	v_lshlrev_b32_e32 v9, 2, v9
	global_load_dword v4, v3, s[20:21] sc1
	global_load_dword v5, v3, s[20:21] offset:256 sc1
	global_load_dword v6, v3, s[20:21] offset:512 sc1
	global_load_dword v7, v3, s[20:21] offset:768 sc1
	global_load_dword v8, v9, s[20:21] sc1
	s_waitcnt vmcnt(0)
	v_cmp_eq_u32_e32 vcc, v4, v8
	s_mov_b64 s[24:25], vcc
	v_cmp_eq_u32_e32 vcc, v5, v8
	s_and_b64 s[24:25], s[24:25], vcc
	v_cmp_eq_u32_e32 vcc, v6, v8
	s_and_b64 s[24:25], s[24:25], vcc
	v_cmp_eq_u32_e32 vcc, v7, v8
	s_and_b64 s[24:25], s[24:25], vcc
	v_cmp_ne_u32_e32 vcc, 0, v8
	s_and_b64 s[24:25], s[24:25], vcc
	s_mov_b32 s16, 2
	s_cmp_eq_u64 s[24:25], exec
	s_cbranch_scc0 .Llb_dec_6
	s_cmpk_eq_i32 s46, 0x100
	s_cbranch_scc0 .Llb_dec_6
	s_mov_b32 s16, 1
.Llb_dec_6:
	s_mov_b64 exec, s[18:19]
	v_mov_b32_e32 v11, s16
	ds_write_b32 v10, v11
	s_waitcnt lgkmcnt(0)
	s_cmp_eq_u32 s16, 1
	s_cbranch_scc0 .Llb_full_6

; __device__ __forceinline__ unsigned xb_ld(unsigned* p)              { return __hip_atomic_load(p, __ATOMIC_RELAXED, __HIP_MEMORY_SCOPE_AGENT); }
; __device__ __forceinline__ unsigned xb_add(unsigned* p, unsigned v) { return __hip_atomic_fetch_add(p, v, __ATOMIC_RELAXED, __HIP_MEMORY_SCOPE_AGENT); }
; __device__ __forceinline__ void xcd_barrier_complete(unsigned* bar, unsigned x, unsigned& nloc, unsigned& nx) {
;     const unsigned G = gridDim.x * gridDim.y * gridDim.z;
;     unsigned sum, cnt, mine, sp = 0u;
;     for (;;) {
;         sum = 0u; cnt = 0u; mine = 0u;
; #pragma unroll
;         for (unsigned j = 0; j < 16; ++j) { const unsigned c = xb_ld(&bar[XB_XCNT(j)]); sum += c; cnt += (c > 0u) ? 1u : 0u; mine = (j == x) ? c : mine; }
; __device__ __forceinline__ void xcd_barrier(const XcdBarrier& b) {
;     asm volatile("s_waitcnt vmcnt(0)" ::: "memory");
;     __syncthreads();
;     if (threadIdx.x == 0) {
;         unsigned* bar = b.bar;
;         __builtin_amdgcn_s_waitcnt(0);
;         unsigned nloc = b.st[0], nx = b.st[1];
;         if (nloc == 0u) { xcd_barrier_complete(bar, b.x, nloc, nx); b.st[0] = nloc; b.st[1] = nx; }
;         const unsigned old = xb_add(&bar[XB_XSUB(b.x)], 1u);
.Llb_full_6:
	v_readlane_b32 s14, v16, 0
	v_readlane_b32 s15, v16, 1
	v_readlane_b32 s16, v16, 2
	v_readlane_b32 s17, v16, 3
	v_readlane_b32 s18, v16, 4
	v_readlane_b32 s19, v16, 5
	v_readlane_b32 s20, v16, 6
	v_readlane_b32 s21, v16, 7
	v_readlane_b32 s22, v16, 8
	v_readlane_b32 s23, v16, 9
	v_readlane_b32 s24, v16, 10
	v_readlane_b32 s25, v16, 11
	s_nop 4
	s_ashr_i32 s15, s14, 31
	s_lshl_b64 s[18:19], s[14:15], 2
	s_add_u32 s12, s12, s18
	s_addc_u32 s13, s13, s19
	s_add_u32 s12, s12, 0x25d00000
	s_addc_u32 s13, s13, 0
	s_add_i32 s29, s14, 0
	s_add_i32 s29, s29, 0x23f00
	v_mov_b32_e32 v0, s29
	s_waitcnt vmcnt(0) expcnt(0) lgkmcnt(0)
	ds_read_b32 v2, v0
	ds_read_b32 v0, v0 offset:4
	s_and_b32 s28, s16, 15
	s_waitcnt lgkmcnt(1)
	v_cmp_ne_u32_e32 vcc, 0, v2
	s_cbranch_vccnz .LBB0_923
	s_add_u32 s14, s12, 0x1000
	s_addc_u32 s15, s13, 0
	s_add_u32 s16, s12, 0x1100
	s_addc_u32 s17, s13, 0
	s_add_u32 s18, s12, 0x1200
	s_addc_u32 s19, s13, 0
	s_mul_i32 s30, s47, s94
	s_add_u32 s20, s12, 0x1300
	s_mul_i32 s30, s30, s46
	s_addc_u32 s21, s13, 0
	s_mov_b32 s31, 1
	v_mov_b32_e32 v16, 0
	s_branch .LBB0_911

; __device__ __forceinline__ unsigned xb_add(unsigned* p, unsigned v) { return __hip_atomic_fetch_add(p, v, __ATOMIC_RELAXED, __HIP_MEMORY_SCOPE_AGENT); }
; __device__ __forceinline__ void xcd_barrier(const XcdBarrier& b) {
;     asm volatile("s_waitcnt vmcnt(0)" ::: "memory");
;     __syncthreads();
;     if (threadIdx.x == 0) {
;         unsigned* bar = b.bar;
;         __builtin_amdgcn_s_waitcnt(0);
;         unsigned nloc = b.st[0], nx = b.st[1];
;         if (nloc == 0u) { xcd_barrier_complete(bar, b.x, nloc, nx); b.st[0] = nloc; b.st[1] = nx; }
;         const unsigned old = xb_add(&bar[XB_XSUB(b.x)], 1u);
.LBB0_1028:
	s_mov_b32 s16, 0
	s_getreg_b32 s10, hwreg(HW_REG_XCC_ID, 0, 4)
	s_waitcnt vmcnt(0)
	s_barrier
	s_and_saveexec_b64 s[12:13], s[4:5]
	s_cbranch_execz .LBB0_1080
	v_writelane_b32 v16, s14, 0
	v_writelane_b32 v16, s15, 1
	v_writelane_b32 v16, s16, 2
	v_writelane_b32 v16, s17, 3
	v_writelane_b32 v16, s18, 4
	v_writelane_b32 v16, s19, 5
	v_writelane_b32 v16, s20, 6
	v_writelane_b32 v16, s21, 7
	v_writelane_b32 v16, s22, 8
	v_writelane_b32 v16, s23, 9
	v_writelane_b32 v16, s24, 10
	v_writelane_b32 v16, s25, 11
	v_mov_b32_e32 v10, 0x23f08
	ds_read_b32 v11, v10
	s_load_dwordx2 s[14:15], s[0:1], 0xc0
	s_waitcnt lgkmcnt(0)
	v_readfirstlane_b32 s16, v11
	s_cmp_eq_u32 s16, 1
	s_cbranch_scc1 .Llb_go_7
	s_cmp_eq_u32 s16, 2
	s_cbranch_scc1 .Llb_full_7
	s_mov_b64 s[18:19], exec
	s_mov_b64 exec, -1
	s_add_u32 s20, s14, 0x25d04000
	s_addc_u32 s21, s15, 0
	v_and_b32_e32 v2, 63, v234
	v_lshlrev_b32_e32 v3, 2, v2
	v_and_b32_e32 v9, 7, v2
	v_lshlrev_b32_e32 v9, 2, v9
	global_load_dword v4, v3, s[20:21] sc1
	global_load_dword v5, v3, s[20:21] offset:256 sc1
	global_load_dword v6, v3, s[20:21] offset:512 sc1
	global_load_dword v7, v3, s[20:21] offset:768 sc1
	global_load_dword v8, v9, s[20:21] sc1
	s_waitcnt vmcnt(0)
	v_cmp_eq_u32_e32 vcc, v4, v8
	s_mov_b64 s[24:25], vcc
	v_cmp_eq_u32_e32 vcc, v5, v8
	s_and_b64 s[24:25], s[24:25], vcc
	v_cmp_eq_u32_e32 vcc, v6, v8
	s_and_b64 s[24:25], s[24:25], vcc
	v_cmp_eq_u32_e32 vcc, v7, v8
	s_and_b64 s[24:25], s[24:25], vcc
	v_cmp_ne_u32_e32 vcc, 0, v8
	s_and_b64 s[24:25], s[24:25], vcc
	s_mov_b32 s16, 2
	s_cmp_eq_u64 s[24:25], exec
	s_cbranch_scc0 .Llb_dec_7
	s_cmpk_eq_i32 s46, 0x100
	s_cbranch_scc0 .Llb_dec_7
	s_mov_b32 s16, 1

; __device__ __forceinline__ unsigned xb_ld(unsigned* p)              { return __hip_atomic_load(p, __ATOMIC_RELAXED, __HIP_MEMORY_SCOPE_AGENT); }
; __device__ __forceinline__ unsigned xb_add(unsigned* p, unsigned v) { return __hip_atomic_fetch_add(p, v, __ATOMIC_RELAXED, __HIP_MEMORY_SCOPE_AGENT); }
; __device__ __forceinline__ void xcd_barrier_complete(unsigned* bar, unsigned x, unsigned& nloc, unsigned& nx) {
;     const unsigned G = gridDim.x * gridDim.y * gridDim.z;
;     unsigned sum, cnt, mine, sp = 0u;
;     for (;;) {
;         sum = 0u; cnt = 0u; mine = 0u;
; #pragma unroll
;         for (unsigned j = 0; j < 16; ++j) { const unsigned c = xb_ld(&bar[XB_XCNT(j)]); sum += c; cnt += (c > 0u) ? 1u : 0u; mine = (j == x) ? c : mine; }
; __device__ __forceinline__ void xcd_barrier(const XcdBarrier& b) {
;     asm volatile("s_waitcnt vmcnt(0)" ::: "memory");
;     __syncthreads();
;     if (threadIdx.x == 0) {
;         unsigned* bar = b.bar;
;         __builtin_amdgcn_s_waitcnt(0);
;         unsigned nloc = b.st[0], nx = b.st[1];
;         if (nloc == 0u) { xcd_barrier_complete(bar, b.x, nloc, nx); b.st[0] = nloc; b.st[1] = nx; }
;         const unsigned old = xb_add(&bar[XB_XSUB(b.x)], 1u);
.Llb_full_7:
	v_readlane_b32 s14, v16, 0
	v_readlane_b32 s15, v16, 1
	v_readlane_b32 s16, v16, 2
	v_readlane_b32 s17, v16, 3
	v_readlane_b32 s18, v16, 4
	v_readlane_b32 s19, v16, 5
	v_readlane_b32 s20, v16, 6
	v_readlane_b32 s21, v16, 7
	v_readlane_b32 s22, v16, 8
	v_readlane_b32 s23, v16, 9
	v_readlane_b32 s24, v16, 10
	v_readlane_b32 s25, v16, 11
	s_nop 4
	s_load_dwordx2 s[14:15], s[0:1], 0xc0
	s_ashr_i32 s17, s16, 31
	s_lshl_b64 s[18:19], s[16:17], 2
	s_waitcnt vmcnt(0) expcnt(0) lgkmcnt(0)
	s_add_u32 s11, s14, s18
	s_addc_u32 s15, s15, s19
	s_add_u32 s14, s11, 0x25d00000
	s_addc_u32 s15, s15, 0
	s_add_i32 s11, s16, 0
	s_add_i32 s11, s11, 0x23f00
	v_mov_b32_e32 v0, s11
	ds_read_b32 v2, v0
	ds_read_b32 v0, v0 offset:4
	s_and_b32 s10, s10, 15
	s_waitcnt lgkmcnt(1)
	v_cmp_ne_u32_e32 vcc, 0, v2
	s_cbranch_vccnz .LBB0_1044
	s_add_u32 s16, s14, 0x1000
	s_addc_u32 s17, s15, 0
	s_add_u32 s18, s14, 0x1100
	s_addc_u32 s19, s15, 0
	s_add_u32 s20, s14, 0x1200
	s_addc_u32 s21, s15, 0
	s_mul_i32 s30, s47, s94
	s_add_u32 s22, s14, 0x1300
	s_mul_i32 s30, s30, s46
	s_addc_u32 s23, s15, 0
	s_mov_b32 s31, 1
	v_mov_b32_e32 v16, 0
	s_branch .LBB0_1032

; __device__ __forceinline__ void ffn_fixup(const Ctx& C, int li) {
;     const float* RB = (const float*)(C.ws + WS_RB); bf16* H = (bf16*)(C.ws + WS_HFF);
;     const float* cw = C.in[16] + (size_t)li * 3 * 2 * DFF; const float* cb = C.in[17] + (size_t)li * 2 * DFF;
;     constexpr int J4 = DFF / 4;
;     for (int idx = C.bid * NTHR + C.tid; idx < 256 * J4; idx += C.G * NTHR) {
;         const int blk = idx / J4, j = (idx % J4) * 4;
;         if ((blk & 31) == 0) continue;
;         f32x4 res[2][2];
.LBB0_1080:
	s_or_b64 exec, exec, s[12:13]
	s_waitcnt lgkmcnt(0)
	v_mov_b32_e32 v0, v234
	s_mov_b32 s12, 0
	s_barrier
	s_load_dwordx2 s[14:15], s[0:1], 0xc0
	s_and_b32 s10, s2, 7
	s_lshl_b32 s10, s10, 5
	s_lshr_b32 s11, s2, 3
	s_add_u32 s10, s10, s11
	s_mul_i32 s10, s10, 0x580
	s_nop 1
	v_add_u32_e32 v2, s10, v0
	s_mov_b32 s10, 0x58000
	v_cmp_gt_i32_e32 vcc, s10, v2
	s_waitcnt lgkmcnt(0)
	v_mov_b64_e32 v[0:1], s[14:15]
	s_and_saveexec_b64 s[16:17], vcc
	s_cbranch_execz .LBB0_1086
	s_ashr_i32 s13, s12, 31
	s_lshl_b64 s[10:11], s[12:13], 3
	s_add_u32 s10, s0, s10
	s_addc_u32 s11, s1, s11
	s_add_u32 s20, s14, s12
	s_addc_u32 s21, s15, s13
	s_load_dwordx4 s[12:15], s[10:11], 0x80
	s_add_u32 s18, s20, 0x1d400000
	s_addc_u32 s19, s21, 0
	s_add_u32 s20, s20, 0x12400000
	s_addc_u32 s21, s21, 0
	s_waitcnt lgkmcnt(0)
	s_add_u32 s22, s12, 0xb000
	s_addc_u32 s23, s13, 0
	s_add_u32 s24, s12, 0x16000
	s_addc_u32 s25, s13, 0
	s_movk_i32 s10, 0x200
	v_lshlrev_b32_e32 v3, 2, v2
	s_movk_i32 s11, 0x800
	s_mov_b64 s[26:27], 0
	s_mov_b32 s30, 0x2e8ba2e9
	s_mov_b32 s31, 0xb000
	v_mov_b32_e32 v1, 0
	s_movk_i32 s33, 0x5000
	s_movk_i32 s34, 0x2c00
	s_and_b32 s35, s2, 7
	s_lshl_b32 s35, s35, 5
	s_lshr_b32 s28, s2, 3
	s_add_u32 s35, s35, s28
	s_mul_i32 s35, s35, 0x580
	s_add_u32 s35, s35, 0x57f
	s_branch .LBB0_1083

; __device__ __forceinline__ unsigned xb_add(unsigned* p, unsigned v) { return __hip_atomic_fetch_add(p, v, __ATOMIC_RELAXED, __HIP_MEMORY_SCOPE_AGENT); }
; __device__ __forceinline__ void xcd_barrier(const XcdBarrier& b) {
;     asm volatile("s_waitcnt vmcnt(0)" ::: "memory");
;     __syncthreads();
;     if (threadIdx.x == 0) {
;         unsigned* bar = b.bar;
;         __builtin_amdgcn_s_waitcnt(0);
;         unsigned nloc = b.st[0], nx = b.st[1];
;         if (nloc == 0u) { xcd_barrier_complete(bar, b.x, nloc, nx); b.st[0] = nloc; b.st[1] = nx; }
;         const unsigned old = xb_add(&bar[XB_XSUB(b.x)], 1u);
.LBB0_1086:
	s_or_b64 exec, exec, s[16:17]
	s_mov_b32 s12, 0
	s_getreg_b32 s10, hwreg(HW_REG_XCC_ID, 0, 4)
	s_waitcnt vmcnt(0)
	s_barrier
	s_and_saveexec_b64 s[52:53], s[4:5]
	s_cbranch_execz .LBB0_1130
	v_writelane_b32 v16, s14, 0
	v_writelane_b32 v16, s15, 1
	v_writelane_b32 v16, s16, 2
	v_writelane_b32 v16, s17, 3
	v_writelane_b32 v16, s18, 4
	v_writelane_b32 v16, s19, 5
	v_writelane_b32 v16, s20, 6
	v_writelane_b32 v16, s21, 7
	v_writelane_b32 v16, s22, 8
	v_writelane_b32 v16, s23, 9
	v_writelane_b32 v16, s24, 10
	v_writelane_b32 v16, s25, 11
	v_mov_b32_e32 v10, 0x23f08
	ds_read_b32 v11, v10
	s_load_dwordx2 s[14:15], s[0:1], 0xc0
	s_waitcnt lgkmcnt(0)
	v_readfirstlane_b32 s16, v11
	s_cmp_eq_u32 s16, 1
	s_cbranch_scc1 .Llb_go_8
	s_cmp_eq_u32 s16, 2
	s_cbranch_scc1 .Llb_full_8
	s_mov_b64 s[18:19], exec
	s_mov_b64 exec, -1
	s_add_u32 s20, s14, 0x25d04000
	s_addc_u32 s21, s15, 0
	v_and_b32_e32 v2, 63, v234
	v_lshlrev_b32_e32 v3, 2, v2
	v_and_b32_e32 v9, 7, v2
	v_lshlrev_b32_e32 v9, 2, v9
	global_load_dword v4, v3, s[20:21] sc1
	global_load_dword v5, v3, s[20:21] offset:256 sc1
	global_load_dword v6, v3, s[20:21] offset:512 sc1
	global_load_dword v7, v3, s[20:21] offset:768 sc1
	global_load_dword v8, v9, s[20:21] sc1
	s_waitcnt vmcnt(0)
	v_cmp_eq_u32_e32 vcc, v4, v8
	s_mov_b64 s[24:25], vcc
	v_cmp_eq_u32_e32 vcc, v5, v8
	s_and_b64 s[24:25], s[24:25], vcc
	v_cmp_eq_u32_e32 vcc, v6, v8
	s_and_b64 s[24:25], s[24:25], vcc
	v_cmp_eq_u32_e32 vcc, v7, v8
	s_and_b64 s[24:25], s[24:25], vcc
	v_cmp_ne_u32_e32 vcc, 0, v8
	s_and_b64 s[24:25], s[24:25], vcc
	s_mov_b32 s16, 2
	s_cmp_eq_u64 s[24:25], exec
	s_cbranch_scc0 .Llb_dec_8
	s_cmpk_eq_i32 s46, 0x100
	s_cbranch_scc0 .Llb_dec_8
	s_mov_b32 s16, 1

; __device__ __forceinline__ unsigned xb_ld(unsigned* p)              { return __hip_atomic_load(p, __ATOMIC_RELAXED, __HIP_MEMORY_SCOPE_AGENT); }
; __device__ __forceinline__ unsigned xb_add(unsigned* p, unsigned v) { return __hip_atomic_fetch_add(p, v, __ATOMIC_RELAXED, __HIP_MEMORY_SCOPE_AGENT); }
; __device__ __forceinline__ void xcd_barrier_complete(unsigned* bar, unsigned x, unsigned& nloc, unsigned& nx) {
;     const unsigned G = gridDim.x * gridDim.y * gridDim.z;
;     unsigned sum, cnt, mine, sp = 0u;
;     for (;;) {
;         sum = 0u; cnt = 0u; mine = 0u;
; #pragma unroll
;         for (unsigned j = 0; j < 16; ++j) { const unsigned c = xb_ld(&bar[XB_XCNT(j)]); sum += c; cnt += (c > 0u) ? 1u : 0u; mine = (j == x) ? c : mine; }
; __device__ __forceinline__ void xcd_barrier(const XcdBarrier& b) {
;     asm volatile("s_waitcnt vmcnt(0)" ::: "memory");
;     __syncthreads();
;     if (threadIdx.x == 0) {
;         unsigned* bar = b.bar;
;         __builtin_amdgcn_s_waitcnt(0);
;         unsigned nloc = b.st[0], nx = b.st[1];
;         if (nloc == 0u) { xcd_barrier_complete(bar, b.x, nloc, nx); b.st[0] = nloc; b.st[1] = nx; }
;         const unsigned old = xb_add(&bar[XB_XSUB(b.x)], 1u);
.Llb_full_8:
	v_readlane_b32 s14, v16, 0
	v_readlane_b32 s15, v16, 1
	v_readlane_b32 s16, v16, 2
	v_readlane_b32 s17, v16, 3
	v_readlane_b32 s18, v16, 4
	v_readlane_b32 s19, v16, 5
	v_readlane_b32 s20, v16, 6
	v_readlane_b32 s21, v16, 7
	v_readlane_b32 s22, v16, 8
	v_readlane_b32 s23, v16, 9
	v_readlane_b32 s24, v16, 10
	v_readlane_b32 s25, v16, 11
	s_nop 4
	s_add_i32 s11, s12, 0
	s_add_i32 s11, s11, 0x23f00
	v_mov_b32_e32 v2, s11
	s_waitcnt vmcnt(0) expcnt(0) lgkmcnt(0)
	ds_read_b32 v4, v2
	ds_read_b32 v6, v2 offset:4
	s_ashr_i32 s13, s12, 31
	v_lshl_add_u64 v[0:1], s[12:13], 2, v[0:1]
	s_mov_b64 s[12:13], 0x25d00000
	s_waitcnt lgkmcnt(1)
	v_cmp_ne_u32_e32 vcc, 0, v4
	v_lshl_add_u64 v[0:1], v[0:1], 0, s[12:13]
	s_and_b32 s10, s10, 15
	s_cbranch_vccnz .LBB0_1101
	s_mov_b64 s[12:13], 0x1000
	v_lshl_add_u64 v[2:3], v[0:1], 0, s[12:13]
	s_mov_b64 s[12:13], 0x1100
	v_lshl_add_u64 v[4:5], v[0:1], 0, s[12:13]
	s_mov_b64 s[12:13], 0x1200
	s_mul_i32 s30, s47, s94
	s_waitcnt lgkmcnt(0)
	v_lshl_add_u64 v[6:7], v[0:1], 0, s[12:13]
	s_mov_b64 s[12:13], 0x1300
	s_mul_i32 s30, s30, s46
	v_lshl_add_u64 v[8:9], v[0:1], 0, s[12:13]
	s_mov_b32 s31, 1
	s_mov_b64 s[12:13], 0
	s_branch .LBB0_1091

; __device__ __forceinline__ unsigned xb_add(unsigned* p, unsigned v) { return __hip_atomic_fetch_add(p, v, __ATOMIC_RELAXED, __HIP_MEMORY_SCOPE_AGENT); }
; __device__ __forceinline__ void xcd_barrier(const XcdBarrier& b) {
;     asm volatile("s_waitcnt vmcnt(0)" ::: "memory");
;     __syncthreads();
;     if (threadIdx.x == 0) {
;         unsigned* bar = b.bar;
;         __builtin_amdgcn_s_waitcnt(0);
;         unsigned nloc = b.st[0], nx = b.st[1];
;         if (nloc == 0u) { xcd_barrier_complete(bar, b.x, nloc, nx); b.st[0] = nloc; b.st[1] = nx; }
;         const unsigned old = xb_add(&bar[XB_XSUB(b.x)], 1u);
.LBB0_1176:
	s_mov_b32 s16, 0
	s_getreg_b32 s10, hwreg(HW_REG_XCC_ID, 0, 4)
	s_waitcnt vmcnt(0)
	s_waitcnt lgkmcnt(0)
	s_barrier
	s_and_saveexec_b64 s[12:13], s[4:5]
	s_cbranch_execz .LBB0_1228
	v_writelane_b32 v16, s14, 0
	v_writelane_b32 v16, s15, 1
	v_writelane_b32 v16, s16, 2
	v_writelane_b32 v16, s17, 3
	v_writelane_b32 v16, s18, 4
	v_writelane_b32 v16, s19, 5
	v_writelane_b32 v16, s20, 6
	v_writelane_b32 v16, s21, 7
	v_writelane_b32 v16, s22, 8
	v_writelane_b32 v16, s23, 9
	v_writelane_b32 v16, s24, 10
	v_writelane_b32 v16, s25, 11
	v_mov_b32_e32 v10, 0x23f08
	ds_read_b32 v11, v10
	s_load_dwordx2 s[14:15], s[0:1], 0xc0
	s_waitcnt lgkmcnt(0)
	v_readfirstlane_b32 s16, v11
	s_cmp_eq_u32 s16, 1
	s_cbranch_scc1 .Llb_go_9
	s_cmp_eq_u32 s16, 2
	s_cbranch_scc1 .Llb_full_9
	s_mov_b64 s[18:19], exec
	s_mov_b64 exec, -1
	s_add_u32 s20, s14, 0x25d04000
	s_addc_u32 s21, s15, 0
	v_and_b32_e32 v2, 63, v234
	v_lshlrev_b32_e32 v3, 2, v2
	v_and_b32_e32 v9, 7, v2
	v_lshlrev_b32_e32 v9, 2, v9
	global_load_dword v4, v3, s[20:21] sc1
	global_load_dword v5, v3, s[20:21] offset:256 sc1
	global_load_dword v6, v3, s[20:21] offset:512 sc1
	global_load_dword v7, v3, s[20:21] offset:768 sc1
	global_load_dword v8, v9, s[20:21] sc1
	s_waitcnt vmcnt(0)
	v_cmp_eq_u32_e32 vcc, v4, v8
	s_mov_b64 s[24:25], vcc
	v_cmp_eq_u32_e32 vcc, v5, v8
	s_and_b64 s[24:25], s[24:25], vcc
	v_cmp_eq_u32_e32 vcc, v6, v8
	s_and_b64 s[24:25], s[24:25], vcc
	v_cmp_eq_u32_e32 vcc, v7, v8
	s_and_b64 s[24:25], s[24:25], vcc
	v_cmp_ne_u32_e32 vcc, 0, v8
	s_and_b64 s[24:25], s[24:25], vcc
	s_mov_b32 s16, 2
	s_cmp_eq_u64 s[24:25], exec
	s_cbranch_scc0 .Llb_dec_9
	s_cmpk_eq_i32 s46, 0x100
	s_cbranch_scc0 .Llb_dec_9
	s_mov_b32 s16, 1

; __device__ __forceinline__ unsigned xb_add(unsigned* p, unsigned v) { return __hip_atomic_fetch_add(p, v, __ATOMIC_RELAXED, __HIP_MEMORY_SCOPE_AGENT); }
; __device__ __forceinline__ void xcd_barrier(const XcdBarrier& b) {
;     asm volatile("s_waitcnt vmcnt(0)" ::: "memory");
;     __syncthreads();
;     if (threadIdx.x == 0) {
;         unsigned* bar = b.bar;
;         __builtin_amdgcn_s_waitcnt(0);
;         unsigned nloc = b.st[0], nx = b.st[1];
;         if (nloc == 0u) { xcd_barrier_complete(bar, b.x, nloc, nx); b.st[0] = nloc; b.st[1] = nx; }
;         const unsigned old = xb_add(&bar[XB_XSUB(b.x)], 1u);
.LBB0_1995:
	s_mov_b32 s16, 0
	s_getreg_b32 s10, hwreg(HW_REG_XCC_ID, 0, 4)
	s_waitcnt vmcnt(0)
	s_waitcnt lgkmcnt(0)
	s_barrier
	s_and_saveexec_b64 s[8:9], s[4:5]
	s_cbranch_execz .LBB0_2047
	v_writelane_b32 v16, s14, 0
	v_writelane_b32 v16, s15, 1
	v_writelane_b32 v16, s16, 2
	v_writelane_b32 v16, s17, 3
	v_writelane_b32 v16, s18, 4
	v_writelane_b32 v16, s19, 5
	v_writelane_b32 v16, s20, 6
	v_writelane_b32 v16, s21, 7
	v_writelane_b32 v16, s22, 8
	v_writelane_b32 v16, s23, 9
	v_writelane_b32 v16, s24, 10
	v_writelane_b32 v16, s25, 11
	v_mov_b32_e32 v10, 0x23f08
	ds_read_b32 v11, v10
	s_load_dwordx2 s[14:15], s[0:1], 0xc0
	s_waitcnt lgkmcnt(0)
	v_readfirstlane_b32 s16, v11
	s_cmp_eq_u32 s16, 1
	s_cbranch_scc1 .Llb_go_15
	s_cmp_eq_u32 s16, 2
	s_cbranch_scc1 .Llb_full_15
	s_mov_b64 s[18:19], exec
	s_mov_b64 exec, -1
	s_add_u32 s20, s14, 0x25d04000
	s_addc_u32 s21, s15, 0
	v_and_b32_e32 v2, 63, v234
	v_lshlrev_b32_e32 v3, 2, v2
	v_and_b32_e32 v9, 7, v2
	v_lshlrev_b32_e32 v9, 2, v9
	global_load_dword v4, v3, s[20:21] sc1
	global_load_dword v5, v3, s[20:21] offset:256 sc1
	global_load_dword v6, v3, s[20:21] offset:512 sc1
	global_load_dword v7, v3, s[20:21] offset:768 sc1
	global_load_dword v8, v9, s[20:21] sc1
	s_waitcnt vmcnt(0)
	v_cmp_eq_u32_e32 vcc, v4, v8
	s_mov_b64 s[24:25], vcc
	v_cmp_eq_u32_e32 vcc, v5, v8
	s_and_b64 s[24:25], s[24:25], vcc
	v_cmp_eq_u32_e32 vcc, v6, v8
	s_and_b64 s[24:25], s[24:25], vcc
	v_cmp_eq_u32_e32 vcc, v7, v8
	s_and_b64 s[24:25], s[24:25], vcc
	v_cmp_ne_u32_e32 vcc, 0, v8
	s_and_b64 s[24:25], s[24:25], vcc
	s_mov_b32 s16, 2
	s_cmp_eq_u64 s[24:25], exec
	s_cbranch_scc0 .Llb_dec_15
	s_cmpk_eq_i32 s46, 0x100
	s_cbranch_scc0 .Llb_dec_15
	s_mov_b32 s16, 1

; __device__ __forceinline__ unsigned xb_ld(unsigned* p)              { return __hip_atomic_load(p, __ATOMIC_RELAXED, __HIP_MEMORY_SCOPE_AGENT); }
; __device__ __forceinline__ unsigned xb_add(unsigned* p, unsigned v) { return __hip_atomic_fetch_add(p, v, __ATOMIC_RELAXED, __HIP_MEMORY_SCOPE_AGENT); }
; __device__ __forceinline__ void xcd_barrier_complete(unsigned* bar, unsigned x, unsigned& nloc, unsigned& nx) {
;     const unsigned G = gridDim.x * gridDim.y * gridDim.z;
;     unsigned sum, cnt, mine, sp = 0u;
;     for (;;) {
;         sum = 0u; cnt = 0u; mine = 0u;
; #pragma unroll
;         for (unsigned j = 0; j < 16; ++j) { const unsigned c = xb_ld(&bar[XB_XCNT(j)]); sum += c; cnt += (c > 0u) ? 1u : 0u; mine = (j == x) ? c : mine; }
; __device__ __forceinline__ void xcd_barrier(const XcdBarrier& b) {
;     asm volatile("s_waitcnt vmcnt(0)" ::: "memory");
;     __syncthreads();
;     if (threadIdx.x == 0) {
;         unsigned* bar = b.bar;
;         __builtin_amdgcn_s_waitcnt(0);
;         unsigned nloc = b.st[0], nx = b.st[1];
;         if (nloc == 0u) { xcd_barrier_complete(bar, b.x, nloc, nx); b.st[0] = nloc; b.st[1] = nx; }
;         const unsigned old = xb_add(&bar[XB_XSUB(b.x)], 1u);
.Llb_full_15:
	v_readlane_b32 s14, v16, 0
	v_readlane_b32 s15, v16, 1
	v_readlane_b32 s16, v16, 2
	v_readlane_b32 s17, v16, 3
	v_readlane_b32 s18, v16, 4
	v_readlane_b32 s19, v16, 5
	v_readlane_b32 s20, v16, 6
	v_readlane_b32 s21, v16, 7
	v_readlane_b32 s22, v16, 8
	v_readlane_b32 s23, v16, 9
	v_readlane_b32 s24, v16, 10
	v_readlane_b32 s25, v16, 11
	s_nop 4
	s_ashr_i32 s17, s16, 31
	s_lshl_b64 s[12:13], s[16:17], 2
	s_add_u32 s11, s14, s12
	s_addc_u32 s13, s15, s13
	s_add_u32 s12, s11, 0x25d00000
	s_addc_u32 s13, s13, 0
	s_add_i32 s11, s16, 0
	s_add_i32 s11, s11, 0x23f00
	v_mov_b32_e32 v0, s11
	s_waitcnt vmcnt(0) expcnt(0) lgkmcnt(0)
	ds_read_b32 v2, v0
	ds_read_b32 v0, v0 offset:4
	s_and_b32 s10, s10, 15
	s_waitcnt lgkmcnt(1)
	v_cmp_ne_u32_e32 vcc, 0, v2
	s_cbranch_vccnz .LBB0_2011
	s_add_u32 s14, s12, 0x1000
	s_addc_u32 s15, s13, 0
	s_add_u32 s16, s12, 0x1100
	s_addc_u32 s17, s13, 0
	s_add_u32 s18, s12, 0x1200
	s_addc_u32 s19, s13, 0
	s_mul_i32 s28, s47, s94
	s_add_u32 s20, s12, 0x1300
	s_mul_i32 s28, s28, s46
	s_addc_u32 s21, s13, 0
	s_mov_b32 s29, 1
	v_mov_b32_e32 v16, 0
	s_branch .LBB0_1999

; __device__ __forceinline__ unsigned xb_add(unsigned* p, unsigned v) { return __hip_atomic_fetch_add(p, v, __ATOMIC_RELAXED, __HIP_MEMORY_SCOPE_AGENT); }
; __device__ __forceinline__ void xcd_barrier(const XcdBarrier& b) {
;     asm volatile("s_waitcnt vmcnt(0)" ::: "memory");
;     __syncthreads();
;     if (threadIdx.x == 0) {
;         unsigned* bar = b.bar;
;         __builtin_amdgcn_s_waitcnt(0);
;         unsigned nloc = b.st[0], nx = b.st[1];
;         if (nloc == 0u) { xcd_barrier_complete(bar, b.x, nloc, nx); b.st[0] = nloc; b.st[1] = nx; }
;         const unsigned old = xb_add(&bar[XB_XSUB(b.x)], 1u);
.LBB0_2116:
	s_mov_b32 s12, 0
	s_getreg_b32 s14, hwreg(HW_REG_XCC_ID, 0, 4)
	s_waitcnt vmcnt(0)
	s_barrier
	s_and_saveexec_b64 s[8:9], s[4:5]
	s_cbranch_execz .LBB0_2168
	v_writelane_b32 v16, s14, 0
	v_writelane_b32 v16, s15, 1
	v_writelane_b32 v16, s16, 2
	v_writelane_b32 v16, s17, 3
	v_writelane_b32 v16, s18, 4
	v_writelane_b32 v16, s19, 5
	v_writelane_b32 v16, s20, 6
	v_writelane_b32 v16, s21, 7
	v_writelane_b32 v16, s22, 8
	v_writelane_b32 v16, s23, 9
	v_writelane_b32 v16, s24, 10
	v_writelane_b32 v16, s25, 11
	v_mov_b32_e32 v10, 0x23f08
	ds_read_b32 v11, v10
	s_load_dwordx2 s[14:15], s[0:1], 0xc0
	s_waitcnt lgkmcnt(0)
	v_readfirstlane_b32 s16, v11
	s_cmp_eq_u32 s16, 1
	s_cbranch_scc1 .Llb_go_16
	s_cmp_eq_u32 s16, 2
	s_cbranch_scc1 .Llb_full_16
	s_mov_b64 s[18:19], exec
	s_mov_b64 exec, -1
	s_add_u32 s20, s14, 0x25d04000
	s_addc_u32 s21, s15, 0
	v_and_b32_e32 v2, 63, v234
	v_lshlrev_b32_e32 v3, 2, v2
	v_and_b32_e32 v9, 7, v2
	v_lshlrev_b32_e32 v9, 2, v9
	global_load_dword v4, v3, s[20:21] sc1
	global_load_dword v5, v3, s[20:21] offset:256 sc1
	global_load_dword v6, v3, s[20:21] offset:512 sc1
	global_load_dword v7, v3, s[20:21] offset:768 sc1
	global_load_dword v8, v9, s[20:21] sc1
	s_waitcnt vmcnt(0)
	v_cmp_eq_u32_e32 vcc, v4, v8
	s_mov_b64 s[24:25], vcc
	v_cmp_eq_u32_e32 vcc, v5, v8
	s_and_b64 s[24:25], s[24:25], vcc
	v_cmp_eq_u32_e32 vcc, v6, v8
	s_and_b64 s[24:25], s[24:25], vcc
	v_cmp_eq_u32_e32 vcc, v7, v8
	s_and_b64 s[24:25], s[24:25], vcc
	v_cmp_ne_u32_e32 vcc, 0, v8
	s_and_b64 s[24:25], s[24:25], vcc
	s_mov_b32 s16, 2
	s_cmp_eq_u64 s[24:25], exec
	s_cbranch_scc0 .Llb_dec_16
	s_cmpk_eq_i32 s46, 0x100
	s_cbranch_scc0 .Llb_dec_16
	s_mov_b32 s16, 1

; __device__ __forceinline__ unsigned xb_ld(unsigned* p)              { return __hip_atomic_load(p, __ATOMIC_RELAXED, __HIP_MEMORY_SCOPE_AGENT); }
; __device__ __forceinline__ unsigned xb_add(unsigned* p, unsigned v) { return __hip_atomic_fetch_add(p, v, __ATOMIC_RELAXED, __HIP_MEMORY_SCOPE_AGENT); }
; __device__ __forceinline__ void xcd_barrier_complete(unsigned* bar, unsigned x, unsigned& nloc, unsigned& nx) {
;     const unsigned G = gridDim.x * gridDim.y * gridDim.z;
;     unsigned sum, cnt, mine, sp = 0u;
;     for (;;) {
;         sum = 0u; cnt = 0u; mine = 0u;
; #pragma unroll
;         for (unsigned j = 0; j < 16; ++j) { const unsigned c = xb_ld(&bar[XB_XCNT(j)]); sum += c; cnt += (c > 0u) ? 1u : 0u; mine = (j == x) ? c : mine; }
; __device__ __forceinline__ void xcd_barrier(const XcdBarrier& b) {
;     asm volatile("s_waitcnt vmcnt(0)" ::: "memory");
;     __syncthreads();
;     if (threadIdx.x == 0) {
;         unsigned* bar = b.bar;
;         __builtin_amdgcn_s_waitcnt(0);
;         unsigned nloc = b.st[0], nx = b.st[1];
;         if (nloc == 0u) { xcd_barrier_complete(bar, b.x, nloc, nx); b.st[0] = nloc; b.st[1] = nx; }
;         const unsigned old = xb_add(&bar[XB_XSUB(b.x)], 1u);
.Llb_full_16:
	v_readlane_b32 s14, v16, 0
	v_readlane_b32 s15, v16, 1
	v_readlane_b32 s16, v16, 2
	v_readlane_b32 s17, v16, 3
	v_readlane_b32 s18, v16, 4
	v_readlane_b32 s19, v16, 5
	v_readlane_b32 s20, v16, 6
	v_readlane_b32 s21, v16, 7
	v_readlane_b32 s22, v16, 8
	v_readlane_b32 s23, v16, 9
	v_readlane_b32 s24, v16, 10
	v_readlane_b32 s25, v16, 11
	s_nop 4
	s_load_dwordx2 s[10:11], s[0:1], 0xc0
	s_ashr_i32 s13, s12, 31
	s_lshl_b64 s[16:17], s[12:13], 2
	s_waitcnt vmcnt(0) expcnt(0) lgkmcnt(0)
	s_add_u32 s10, s10, s16
	s_addc_u32 s11, s11, s17
	s_add_u32 s10, s10, 0x25d00000
	s_addc_u32 s11, s11, 0
	s_add_i32 s27, s12, 0
	s_add_i32 s27, s27, 0x23f00
	v_mov_b32_e32 v0, s27
	ds_read_b32 v2, v0
	ds_read_b32 v0, v0 offset:4
	s_and_b32 s26, s14, 15
	s_waitcnt lgkmcnt(1)
	v_cmp_ne_u32_e32 vcc, 0, v2
	s_cbranch_vccnz .LBB0_2132
	s_add_u32 s12, s10, 0x1000
	s_addc_u32 s13, s11, 0
	s_add_u32 s14, s10, 0x1100
	s_addc_u32 s15, s11, 0
	s_add_u32 s16, s10, 0x1200
	s_addc_u32 s17, s11, 0
	s_mul_i32 s28, s47, s94
	s_add_u32 s18, s10, 0x1300
	s_mul_i32 s28, s28, s46
	s_addc_u32 s19, s11, 0
	s_mov_b32 s29, 1
	v_mov_b32_e32 v16, 0
	s_branch .LBB0_2120

; __device__ __forceinline__ void ffn_fixup(const Ctx& C, int li) {
;     const float* RB = (const float*)(C.ws + WS_RB); bf16* H = (bf16*)(C.ws + WS_HFF);
;     const float* cw = C.in[16] + (size_t)li * 3 * 2 * DFF; const float* cb = C.in[17] + (size_t)li * 2 * DFF;
;     constexpr int J4 = DFF / 4;
;     for (int idx = C.bid * NTHR + C.tid; idx < 256 * J4; idx += C.G * NTHR) {
;         const int blk = idx / J4, j = (idx % J4) * 4;
;         if ((blk & 31) == 0) continue;
;         f32x4 res[2][2];
.LBB0_2168:
	s_or_b64 exec, exec, s[8:9]
	s_waitcnt lgkmcnt(0)
	v_mov_b32_e32 v0, v234
	s_mov_b32 s10, 0
	s_barrier
	s_load_dwordx2 s[12:13], s[0:1], 0xc0
	s_and_b32 s8, s2, 7
	s_lshl_b32 s8, s8, 5
	s_lshr_b32 s9, s2, 3
	s_add_u32 s8, s8, s9
	s_mul_i32 s8, s8, 0x580
	s_nop 1
	v_add_u32_e32 v2, s8, v0
	s_mov_b32 s8, 0x58000
	v_cmp_gt_i32_e32 vcc, s8, v2
	s_waitcnt lgkmcnt(0)
	v_mov_b64_e32 v[0:1], s[12:13]
	s_and_saveexec_b64 s[8:9], vcc
	s_cbranch_execz .LBB0_2174
	s_ashr_i32 s11, s10, 31
	s_lshl_b64 s[14:15], s[10:11], 3
	s_add_u32 s14, s0, s14
	s_addc_u32 s15, s1, s15
	s_add_u32 s12, s12, s10
	s_addc_u32 s13, s13, s11
	s_load_dwordx4 s[20:23], s[14:15], 0x80
	s_add_u32 s10, s12, 0x1d400000
	s_addc_u32 s11, s13, 0
	s_add_u32 s12, s12, 0x12400000
	s_addc_u32 s13, s13, 0
	s_waitcnt lgkmcnt(0)
	s_add_u32 s14, s20, 0x21000
	s_addc_u32 s15, s21, 0
	s_add_u32 s16, s22, 0xb000
	s_addc_u32 s17, s23, 0
	s_add_u32 s18, s20, 0x2c000
	s_addc_u32 s19, s21, 0
	s_add_u32 s20, s20, 0x37000
	s_addc_u32 s21, s21, 0
	s_movk_i32 s26, 0x200
	v_lshlrev_b32_e32 v3, 2, v2
	s_movk_i32 s27, 0x800
	s_mov_b64 s[22:23], 0
	s_mov_b32 s28, 0x2e8ba2e9
	s_mov_b32 s29, 0xb000
	v_mov_b32_e32 v1, 0
	s_movk_i32 s30, 0x5000
	s_movk_i32 s31, 0x2c00
	s_and_b32 s33, s2, 7
	s_lshl_b32 s33, s33, 5
	s_lshr_b32 s24, s2, 3
	s_add_u32 s33, s33, s24
	s_mul_i32 s33, s33, 0x580
	s_add_u32 s33, s33, 0x57f
	s_branch .LBB0_2171

; __device__ __forceinline__ unsigned xb_add(unsigned* p, unsigned v) { return __hip_atomic_fetch_add(p, v, __ATOMIC_RELAXED, __HIP_MEMORY_SCOPE_AGENT); }
; __device__ __forceinline__ void xcd_barrier(const XcdBarrier& b) {
;     asm volatile("s_waitcnt vmcnt(0)" ::: "memory");
;     __syncthreads();
;     if (threadIdx.x == 0) {
;         unsigned* bar = b.bar;
;         __builtin_amdgcn_s_waitcnt(0);
;         unsigned nloc = b.st[0], nx = b.st[1];
;         if (nloc == 0u) { xcd_barrier_complete(bar, b.x, nloc, nx); b.st[0] = nloc; b.st[1] = nx; }
;         const unsigned old = xb_add(&bar[XB_XSUB(b.x)], 1u);
.LBB0_2174:
	s_or_b64 exec, exec, s[8:9]
	s_mov_b32 s8, 0
	s_getreg_b32 s10, hwreg(HW_REG_XCC_ID, 0, 4)
	s_waitcnt vmcnt(0)
	s_barrier
	s_and_saveexec_b64 s[40:41], s[4:5]
	s_cbranch_execz .LBB0_2218
	v_writelane_b32 v16, s14, 0
	v_writelane_b32 v16, s15, 1
	v_writelane_b32 v16, s16, 2
	v_writelane_b32 v16, s17, 3
	v_writelane_b32 v16, s18, 4
	v_writelane_b32 v16, s19, 5
	v_writelane_b32 v16, s20, 6
	v_writelane_b32 v16, s21, 7
	v_writelane_b32 v16, s22, 8
	v_writelane_b32 v16, s23, 9
	v_writelane_b32 v16, s24, 10
	v_writelane_b32 v16, s25, 11
	v_mov_b32_e32 v10, 0x23f08
	ds_read_b32 v11, v10
	s_load_dwordx2 s[14:15], s[0:1], 0xc0
	s_waitcnt lgkmcnt(0)
	v_readfirstlane_b32 s16, v11
	s_cmp_eq_u32 s16, 1
	s_cbranch_scc1 .Llb_go_17
	s_cmp_eq_u32 s16, 2
	s_cbranch_scc1 .Llb_full_17
	s_mov_b64 s[18:19], exec
	s_mov_b64 exec, -1
	s_add_u32 s20, s14, 0x25d04000
	s_addc_u32 s21, s15, 0
	v_and_b32_e32 v2, 63, v234
	v_lshlrev_b32_e32 v3, 2, v2
	v_and_b32_e32 v9, 7, v2
	v_lshlrev_b32_e32 v9, 2, v9
	global_load_dword v4, v3, s[20:21] sc1
	global_load_dword v5, v3, s[20:21] offset:256 sc1
	global_load_dword v6, v3, s[20:21] offset:512 sc1
	global_load_dword v7, v3, s[20:21] offset:768 sc1
	global_load_dword v8, v9, s[20:21] sc1
	s_waitcnt vmcnt(0)
	v_cmp_eq_u32_e32 vcc, v4, v8
	s_mov_b64 s[24:25], vcc
	v_cmp_eq_u32_e32 vcc, v5, v8
	s_and_b64 s[24:25], s[24:25], vcc
	v_cmp_eq_u32_e32 vcc, v6, v8
	s_and_b64 s[24:25], s[24:25], vcc
	v_cmp_eq_u32_e32 vcc, v7, v8
	s_and_b64 s[24:25], s[24:25], vcc
	v_cmp_ne_u32_e32 vcc, 0, v8
	s_and_b64 s[24:25], s[24:25], vcc
	s_mov_b32 s16, 2
	s_cmp_eq_u64 s[24:25], exec
	s_cbranch_scc0 .Llb_dec_17
	s_cmpk_eq_i32 s46, 0x100
	s_cbranch_scc0 .Llb_dec_17
	s_mov_b32 s16, 1

; __device__ __forceinline__ unsigned xb_ld(unsigned* p)              { return __hip_atomic_load(p, __ATOMIC_RELAXED, __HIP_MEMORY_SCOPE_AGENT); }
; __device__ __forceinline__ unsigned xb_add(unsigned* p, unsigned v) { return __hip_atomic_fetch_add(p, v, __ATOMIC_RELAXED, __HIP_MEMORY_SCOPE_AGENT); }
; __device__ __forceinline__ void xcd_barrier_complete(unsigned* bar, unsigned x, unsigned& nloc, unsigned& nx) {
;     const unsigned G = gridDim.x * gridDim.y * gridDim.z;
;     unsigned sum, cnt, mine, sp = 0u;
;     for (;;) {
;         sum = 0u; cnt = 0u; mine = 0u;
; #pragma unroll
;         for (unsigned j = 0; j < 16; ++j) { const unsigned c = xb_ld(&bar[XB_XCNT(j)]); sum += c; cnt += (c > 0u) ? 1u : 0u; mine = (j == x) ? c : mine; }
; __device__ __forceinline__ void xcd_barrier(const XcdBarrier& b) {
;     asm volatile("s_waitcnt vmcnt(0)" ::: "memory");
;     __syncthreads();
;     if (threadIdx.x == 0) {
;         unsigned* bar = b.bar;
;         __builtin_amdgcn_s_waitcnt(0);
;         unsigned nloc = b.st[0], nx = b.st[1];
;         if (nloc == 0u) { xcd_barrier_complete(bar, b.x, nloc, nx); b.st[0] = nloc; b.st[1] = nx; }
;         const unsigned old = xb_add(&bar[XB_XSUB(b.x)], 1u);
.Llb_full_17:
	v_readlane_b32 s14, v16, 0
	v_readlane_b32 s15, v16, 1
	v_readlane_b32 s16, v16, 2
	v_readlane_b32 s17, v16, 3
	v_readlane_b32 s18, v16, 4
	v_readlane_b32 s19, v16, 5
	v_readlane_b32 s20, v16, 6
	v_readlane_b32 s21, v16, 7
	v_readlane_b32 s22, v16, 8
	v_readlane_b32 s23, v16, 9
	v_readlane_b32 s24, v16, 10
	v_readlane_b32 s25, v16, 11
	s_nop 4
	s_add_i32 s42, s8, 0
	s_add_i32 s42, s42, 0x23f00
	v_mov_b32_e32 v2, s42
	s_waitcnt vmcnt(0) expcnt(0) lgkmcnt(0)
	ds_read_b32 v4, v2
	ds_read_b32 v6, v2 offset:4
	s_ashr_i32 s9, s8, 31
	v_lshl_add_u64 v[0:1], s[8:9], 2, v[0:1]
	s_mov_b64 s[8:9], 0x25d00000
	s_waitcnt lgkmcnt(1)
	v_cmp_ne_u32_e32 vcc, 0, v4
	v_lshl_add_u64 v[0:1], v[0:1], 0, s[8:9]
	s_and_b32 s33, s10, 15
	s_cbranch_vccnz .LBB0_2189
	s_mov_b64 s[8:9], 0x1000
	v_lshl_add_u64 v[2:3], v[0:1], 0, s[8:9]
	s_mov_b64 s[8:9], 0x1100
	v_lshl_add_u64 v[4:5], v[0:1], 0, s[8:9]
	s_mov_b64 s[8:9], 0x1200
	s_mul_i32 s26, s47, s94
	s_waitcnt lgkmcnt(0)
	v_lshl_add_u64 v[6:7], v[0:1], 0, s[8:9]
	s_mov_b64 s[8:9], 0x1300
	s_mul_i32 s26, s26, s46
	v_lshl_add_u64 v[8:9], v[0:1], 0, s[8:9]
	s_mov_b32 s27, 1
	s_mov_b64 s[8:9], 0
	s_branch .LBB0_2179

; __device__ __forceinline__ unsigned xb_add(unsigned* p, unsigned v) { return __hip_atomic_fetch_add(p, v, __ATOMIC_RELAXED, __HIP_MEMORY_SCOPE_AGENT); }
; __device__ __forceinline__ void xcd_barrier(const XcdBarrier& b) {
;     asm volatile("s_waitcnt vmcnt(0)" ::: "memory");
;     __syncthreads();
;     if (threadIdx.x == 0) {
;         unsigned* bar = b.bar;
;         __builtin_amdgcn_s_waitcnt(0);
;         unsigned nloc = b.st[0], nx = b.st[1];
;         if (nloc == 0u) { xcd_barrier_complete(bar, b.x, nloc, nx); b.st[0] = nloc; b.st[1] = nx; }
;         const unsigned old = xb_add(&bar[XB_XSUB(b.x)], 1u);
.LBB0_2264:
	s_mov_b32 s12, 0
	s_getreg_b32 s14, hwreg(HW_REG_XCC_ID, 0, 4)
	s_waitcnt vmcnt(0)
	s_waitcnt lgkmcnt(0)
	s_barrier
	s_and_saveexec_b64 s[8:9], s[4:5]
	s_cbranch_execz .LBB0_2316
	v_writelane_b32 v16, s14, 0
	v_writelane_b32 v16, s15, 1
	v_writelane_b32 v16, s16, 2
	v_writelane_b32 v16, s17, 3
	v_writelane_b32 v16, s18, 4
	v_writelane_b32 v16, s19, 5
	v_writelane_b32 v16, s20, 6
	v_writelane_b32 v16, s21, 7
	v_writelane_b32 v16, s22, 8
	v_writelane_b32 v16, s23, 9
	v_writelane_b32 v16, s24, 10
	v_writelane_b32 v16, s25, 11
	v_mov_b32_e32 v10, 0x23f08
	ds_read_b32 v11, v10
	s_load_dwordx2 s[14:15], s[0:1], 0xc0
	s_waitcnt lgkmcnt(0)
	v_readfirstlane_b32 s16, v11
	s_cmp_eq_u32 s16, 1
	s_cbranch_scc1 .Llb_go_18
	s_cmp_eq_u32 s16, 2
	s_cbranch_scc1 .Llb_full_18
	s_mov_b64 s[18:19], exec
	s_mov_b64 exec, -1
	s_add_u32 s20, s14, 0x25d04000
	s_addc_u32 s21, s15, 0
	v_and_b32_e32 v2, 63, v234
	v_lshlrev_b32_e32 v3, 2, v2
	v_and_b32_e32 v9, 7, v2
	v_lshlrev_b32_e32 v9, 2, v9
	global_load_dword v4, v3, s[20:21] sc1
	global_load_dword v5, v3, s[20:21] offset:256 sc1
	global_load_dword v6, v3, s[20:21] offset:512 sc1
	global_load_dword v7, v3, s[20:21] offset:768 sc1
	global_load_dword v8, v9, s[20:21] sc1
	s_waitcnt vmcnt(0)
	v_cmp_eq_u32_e32 vcc, v4, v8
	s_mov_b64 s[24:25], vcc
	v_cmp_eq_u32_e32 vcc, v5, v8
	s_and_b64 s[24:25], s[24:25], vcc
	v_cmp_eq_u32_e32 vcc, v6, v8
	s_and_b64 s[24:25], s[24:25], vcc
	v_cmp_eq_u32_e32 vcc, v7, v8
	s_and_b64 s[24:25], s[24:25], vcc
	v_cmp_ne_u32_e32 vcc, 0, v8
	s_and_b64 s[24:25], s[24:25], vcc
	s_mov_b32 s16, 2
	s_cmp_eq_u64 s[24:25], exec
	s_cbranch_scc0 .Llb_dec_18
	s_cmpk_eq_i32 s46, 0x100
	s_cbranch_scc0 .Llb_dec_18
	s_mov_b32 s16, 1

; __device__ __forceinline__ unsigned xb_ld(unsigned* p)              { return __hip_atomic_load(p, __ATOMIC_RELAXED, __HIP_MEMORY_SCOPE_AGENT); }
; __device__ __forceinline__ unsigned xb_add(unsigned* p, unsigned v) { return __hip_atomic_fetch_add(p, v, __ATOMIC_RELAXED, __HIP_MEMORY_SCOPE_AGENT); }
; __device__ __forceinline__ void xcd_barrier_complete(unsigned* bar, unsigned x, unsigned& nloc, unsigned& nx) {
;     const unsigned G = gridDim.x * gridDim.y * gridDim.z;
;     unsigned sum, cnt, mine, sp = 0u;
;     for (;;) {
;         sum = 0u; cnt = 0u; mine = 0u;
; #pragma unroll
;         for (unsigned j = 0; j < 16; ++j) { const unsigned c = xb_ld(&bar[XB_XCNT(j)]); sum += c; cnt += (c > 0u) ? 1u : 0u; mine = (j == x) ? c : mine; }
; __device__ __forceinline__ void xcd_barrier(const XcdBarrier& b) {
;     asm volatile("s_waitcnt vmcnt(0)" ::: "memory");
;     __syncthreads();
;     if (threadIdx.x == 0) {
;         unsigned* bar = b.bar;
;         __builtin_amdgcn_s_waitcnt(0);
;         unsigned nloc = b.st[0], nx = b.st[1];
;         if (nloc == 0u) { xcd_barrier_complete(bar, b.x, nloc, nx); b.st[0] = nloc; b.st[1] = nx; }
;         const unsigned old = xb_add(&bar[XB_XSUB(b.x)], 1u);
.Llb_full_18:
	v_readlane_b32 s14, v16, 0
	v_readlane_b32 s15, v16, 1
	v_readlane_b32 s16, v16, 2
	v_readlane_b32 s17, v16, 3
	v_readlane_b32 s18, v16, 4
	v_readlane_b32 s19, v16, 5
	v_readlane_b32 s20, v16, 6
	v_readlane_b32 s21, v16, 7
	v_readlane_b32 s22, v16, 8
	v_readlane_b32 s23, v16, 9
	v_readlane_b32 s24, v16, 10
	v_readlane_b32 s25, v16, 11
	s_nop 4
	s_ashr_i32 s13, s12, 31
	s_lshl_b64 s[16:17], s[12:13], 2
	s_add_u32 s10, s10, s16
	s_addc_u32 s11, s11, s17
	s_add_u32 s10, s10, 0x25d00000
	s_addc_u32 s11, s11, 0
	s_add_i32 s27, s12, 0
	s_add_i32 s27, s27, 0x23f00
	v_mov_b32_e32 v0, s27
	s_waitcnt vmcnt(0) expcnt(0) lgkmcnt(0)
	ds_read_b32 v2, v0
	ds_read_b32 v0, v0 offset:4
	s_and_b32 s26, s14, 15
	s_waitcnt lgkmcnt(1)
	v_cmp_ne_u32_e32 vcc, 0, v2
	s_cbranch_vccnz .LBB0_2280
	s_add_u32 s12, s10, 0x1000
	s_addc_u32 s13, s11, 0
	s_add_u32 s14, s10, 0x1100
	s_addc_u32 s15, s11, 0
	s_add_u32 s16, s10, 0x1200
	s_addc_u32 s17, s11, 0
	s_mul_i32 s28, s47, s94
	s_add_u32 s18, s10, 0x1300
	s_mul_i32 s28, s28, s46
	s_addc_u32 s19, s11, 0
	s_mov_b32 s29, 1
	v_mov_b32_e32 v16, 0
	s_branch .LBB0_2268
